# phase 12: grid barrier between attention and gate replaced by split-phase lnstat counter (release after lnstat, acquire before gate)
# speedup vs baseline: 1.0040x; 1.0040x over previous
.LBB0_1634:
	v_writelane_b32 v254, s42, 53
	s_nop 1
	v_writelane_b32 v254, s43, 54
	v_writelane_b32 v254, s34, 55
	s_nop 1
	v_writelane_b32 v254, s35, 56
	v_writelane_b32 v254, s30, 57
	s_nop 1
	v_writelane_b32 v254, s31, 58
	v_writelane_b32 v254, s28, 59
	s_nop 1
	v_writelane_b32 v254, s29, 60
	v_writelane_b32 v254, s26, 61
	s_nop 1
	v_writelane_b32 v254, s27, 62
	s_or_b64 exec, exec, s[0:1]
	s_waitcnt vmcnt(0)
	s_barrier
	s_mov_b64 s[0:1], exec
	v_readlane_b32 s2, v253, 0
	v_readlane_b32 s3, v253, 1
	s_and_b64 s[2:3], s[0:1], s[2:3]
	s_mov_b64 exec, s[2:3]
	s_cbranch_execz .Lp12a_done
	buffer_wbl2 sc1
	s_waitcnt vmcnt(0)
	s_add_u32 s2, s88, 0xfc02400
	s_addc_u32 s3, s89, 0
	v_mov_b32_e32 v0, 0
	v_mov_b32_e32 v1, 1
	global_atomic_add v0, v1, s[2:3]
	s_waitcnt vmcnt(0)
.Lp12a_done:
	s_mov_b64 exec, s[0:1]
	s_add_u32 s42, s88, 0x7800000
	s_addc_u32 s43, s89, 0
	v_readlane_b32 s0, v253, 6
	v_and_b32_e32 v143, 15, v196
	v_bfe_u32 v107, v196, 4, 2
	s_cmpk_gt_i32 s0, 0x5ff
	v_lshlrev_b32_e32 v144, 3, v107
	v_mov_b32_e32 v105, 0
	v_add_u32_e32 v150, 0x100, v196
	v_add_u32_e32 v149, 0x200, v196
	v_add_u32_e32 v148, 0x300, v196
	v_lshlrev_b32_e32 v145, 4, v107
	s_movk_i32 s0, 0x110
	v_mul_u32_u24_e32 v147, 0x110, v143
	v_or_b32_e32 v146, 16, v143
	s_cbranch_scc1 .LBB0_1657
	s_add_u32 s70, s88, 0x124000
	s_addc_u32 s71, s89, 0
	s_add_u32 s94, s88, 0x24000
	v_writelane_b32 v254, s10, 63
	s_addc_u32 s95, s89, 0
	s_add_u32 s19, s88, 0xcc00000
	v_writelane_b32 v255, s11, 0
	v_writelane_b32 v255, s20, 1
	v_lshlrev_b32_e32 v0, 3, v196
	s_movk_i32 s1, 0x900
	v_writelane_b32 v255, s21, 2
	s_addc_u32 s20, s89, 0
	s_add_u32 s21, s88, 0x1a4000
	v_and_b32_e32 v106, 56, v0
	v_lshlrev_b32_e32 v156, 2, v107
	v_lshlrev_b32_e32 v104, 1, v143
	v_mad_u32_u24 v0, v142, s1, 16
	v_mul_u32_u24_e32 v158, 0x90, v143
	v_lshlrev_b32_e32 v108, 1, v144
	s_addc_u32 s22, s89, 0
	v_lshrrev_b32_e32 v152, 3, v196
	v_lshrrev_b32_e32 v153, 3, v150
	v_lshrrev_b32_e32 v154, 3, v149
	v_lshrrev_b32_e32 v155, 3, v148
	v_lshl_add_u32 v2, v106, 1, 16
	v_add_u32_e32 v3, v0, v104
	v_add3_u32 v159, v0, v158, v108
	v_sub_u32_e32 v0, v156, v143
	s_add_u32 s2, s88, 0xa4000
	v_add_u32_e32 v157, 16, v145
	v_mad_u32_u24 v160, v152, s0, v2
	v_mad_u32_u24 v161, v153, s0, v2
	v_mul_u32_u24_e32 v4, 0x90, v152
	v_mul_u32_u24_e32 v5, 0x90, v153
	v_mul_u32_u24_e32 v6, 0x90, v154
	v_mul_u32_u24_e32 v7, 0x90, v155
	v_mul_u32_u24_e32 v8, 0x240, v107
	v_mul_u32_u24_e32 v9, 0x90, v146
	v_add_u32_e32 v162, 0xffffff7f, v0
	s_addc_u32 s3, s89, 0
	v_lshl_add_u64 v[0:1], s[88:89], 0, v[104:105]
	s_mov_b64 s[0:1], 0x1840800
	v_lshlrev_b32_e32 v104, 2, v106
	v_lshlrev_b32_e32 v151, 4, v142
	v_lshl_add_u64 v[110:111], v[0:1], 0, s[0:1]
	v_lshl_add_u64 v[112:113], s[94:95], 0, v[104:105]
	v_lshl_add_u64 v[114:115], s[2:3], 0, v[104:105]
	v_add_u32_e32 v163, 64, v152
	v_add_u32_e32 v164, 64, v153
	v_add_u32_e32 v165, 0xffff8040, v153
	v_add_u32_e32 v166, 0xffff8040, v152
	s_mov_b32 s97, 0
	s_movk_i32 s23, 0x1c00
	v_mov_b64_e32 v[116:117], s[42:43]
	v_mov_b32_e32 v109, v105
	s_mov_b64 s[0:1], 0x1800
	v_add_u32_e32 v167, v2, v4
	s_waitcnt vmcnt(8)
	v_add_u32_e32 v168, v2, v5
	v_add_u32_e32 v169, v2, v6
	v_add_u32_e32 v170, v2, v7
	s_movk_i32 s24, 0xfeff
	s_mov_b32 s25, 0xf149f2ca
	v_add_u32_e32 v171, v3, v8
	v_add_u32_e32 v172, v157, v9
	v_mov_b32_e32 v173, 0xf149f2ca
	v_readlane_b32 s26, v253, 6
	s_branch .LBB0_1638

.LBB0_1657:
	s_waitcnt vmcnt(0)
	s_waitcnt lgkmcnt(0)
	s_barrier
	s_mov_b64 s[0:1], exec
	v_readlane_b32 s2, v253, 0
	v_readlane_b32 s3, v253, 1
	s_and_b64 s[2:3], s[0:1], s[2:3]
	s_mov_b64 exec, s[2:3]
	s_cbranch_execz .LBB0_1709
	s_add_u32 s4, s88, 0xfc02400
	s_addc_u32 s5, s89, 0
	v_mov_b32_e32 v16, 0
	s_mov_b32 s6, 0
.Lp12w_spin:
	global_load_dword v17, v16, s[4:5] sc1
	s_waitcnt vmcnt(0)
	v_cmp_gt_u32_e32 vcc, 0x200, v17
	s_cbranch_vccz .Lp12w_done
	s_add_i32 s6, s6, 1
	s_cmp_lt_u32 s6, 0x100000
	s_cbranch_scc0 .Lp12w_done
	s_sleep 1
	s_branch .Lp12w_spin
.Lp12w_done:
	buffer_inv sc1
.LBB0_1709:
	s_or_b64 exec, exec, s[0:1]
	v_readlane_b32 s0, v253, 39
	v_readlane_b32 s84, v253, 6
	v_readlane_b32 s52, v253, 55
	v_readlane_b32 s14, v253, 53
	v_readlane_b32 s15, v253, 54
	v_lshrrev_b32_e32 v76, 4, v196
	s_cmpk_gt_i32 s84, 0x2ff
	v_readlane_b32 s62, v254, 1
	v_readlane_b32 s63, v254, 2
	v_readlane_b32 s64, v254, 3
	v_readlane_b32 s65, v254, 4
	v_readlane_b32 s66, v254, 5
	v_readlane_b32 s67, v254, 6
	v_readlane_b32 s4, v253, 43
	v_readlane_b32 s5, v253, 44
	v_readlane_b32 s6, v253, 45
	v_readlane_b32 s7, v253, 46
	v_readlane_b32 s10, v253, 49
	v_readlane_b32 s11, v253, 50
	s_mov_b64 s[78:79], s[14:15]
	s_waitcnt lgkmcnt(0)
	s_barrier
	v_readlane_b32 s53, v253, 56
	v_readlane_b32 s54, v253, 57
	v_readlane_b32 s55, v253, 58
	v_readlane_b32 s56, v253, 59
	v_readlane_b32 s57, v253, 60
	v_readlane_b32 s58, v253, 61
	v_readlane_b32 s59, v253, 62
	v_readlane_b32 s60, v253, 63
	v_readlane_b32 s61, v254, 0
	v_readlane_b32 s1, v253, 40
	v_readlane_b32 s2, v253, 41
	v_readlane_b32 s3, v253, 42
	v_readlane_b32 s8, v253, 47
	v_readlane_b32 s9, v253, 48
	v_readlane_b32 s12, v253, 51
	v_readlane_b32 s13, v253, 52
	s_cbranch_scc1 .LBB0_1712
	v_and_b32_e32 v0, 7, v76
	v_lshrrev_b32_e32 v2, 7, v196
	v_mul_u32_u24_e32 v4, 0x440, v143
	v_xor_b32_e32 v2, v2, v143
	v_lshlrev_b32_e32 v0, 1, v0
	v_lshlrev_b32_e32 v4, 1, v4
	v_lshl_or_b32 v2, v2, 4, v0
	v_add_u32_e32 v5, 16, v4
	v_add3_u32 v78, 16, v2, v4
	v_add_u32_e32 v79, v5, v2
	v_lshrrev_b32_e32 v2, 7, v150
	v_xor_b32_e32 v2, v2, v143
	v_lshl_or_b32 v2, v2, 4, v0
	v_add3_u32 v81, 16, v2, v4
	v_add_u32_e32 v82, v5, v2
	v_lshrrev_b32_e32 v2, 7, v149
	v_xor_b32_e32 v2, v2, v143
	v_lshl_or_b32 v2, v2, 4, v0
	v_add3_u32 v84, 16, v2, v4
	v_add_u32_e32 v85, v5, v2
	v_lshrrev_b32_e32 v2, 7, v148
	v_xor_b32_e32 v2, v2, v143
	v_lshl_or_b32 v2, v2, 4, v0
	v_add3_u32 v87, 16, v2, v4
	v_add_u32_e32 v88, v5, v2
	v_or_b32_e32 v2, 0x400, v196
	v_lshrrev_b32_e32 v89, 4, v2
	v_lshrrev_b32_e32 v2, 7, v2
	v_xor_b32_e32 v2, v2, v143
	v_lshl_or_b32 v2, v2, 4, v0
	v_add3_u32 v90, 16, v2, v4
	v_add_u32_e32 v91, v5, v2
	v_add_u32_e32 v2, 0x500, v196
	v_lshrrev_b32_e32 v92, 4, v2
	v_lshrrev_b32_e32 v2, 7, v2
	v_xor_b32_e32 v2, v2, v143
	v_lshl_or_b32 v2, v2, 4, v0
	v_add3_u32 v93, 16, v2, v4
	v_add_u32_e32 v94, v5, v2
	v_add_u32_e32 v2, 0x600, v196
	v_lshrrev_b32_e32 v95, 4, v2
	v_lshrrev_b32_e32 v2, 7, v2
	v_xor_b32_e32 v2, v2, v143
	v_lshl_or_b32 v2, v2, 4, v0
	v_add3_u32 v96, 16, v2, v4
	v_add_u32_e32 v97, v5, v2
	v_add_u32_e32 v2, 0x700, v196
	v_lshrrev_b32_e32 v98, 4, v2
	v_lshrrev_b32_e32 v2, 7, v2
	v_xor_b32_e32 v2, v2, v143
	v_lshl_or_b32 v0, v2, 4, v0
	v_add3_u32 v99, 16, v0, v4
	v_add_u32_e32 v4, 16, v147
	v_bitop3_b32 v6, v144, v196, 8 bitop3:0x78
	v_or_b32_e32 v1, 32, v143
	v_lshl_add_u32 v101, v6, 1, v4
	v_add_u32_e32 v6, 0x1100, v4
	v_bitop3_b32 v8, v146, v144, 24 bitop3:0x6c
	v_or_b32_e32 v3, 48, v143
	v_lshl_add_u32 v102, v8, 1, v6
	v_add_u32_e32 v8, 0x2200, v4
	v_bitop3_b32 v1, v1, v144, 40 bitop3:0x6c
	v_lshl_add_u32 v103, v1, 1, v8
	v_add_u32_e32 v1, 0x3300, v4
	v_bitop3_b32 v3, v3, v144, 56 bitop3:0x6c
	v_lshl_add_u32 v104, v3, 1, v1
	v_or_b32_e32 v3, 64, v143
	s_movk_i32 s0, 0x110
	v_mad_u32_u24 v11, v3, s0, 16
	s_movk_i32 s0, 0x48
	v_bitop3_b32 v3, v3, v144, s0 bitop3:0x6c
	v_bitop3_b32 v12, v143, s0, 64 bitop3:0xc8
	v_lshl_add_u32 v105, v3, 1, v11
	v_or_b32_e32 v3, 0x50, v143
	s_movk_i32 s0, 0x58
	v_add_u32_e32 v13, 0x1100, v11
	v_bitop3_b32 v3, v3, v144, s0 bitop3:0x6c
	v_lshl_add_u32 v106, v3, 1, v13
	v_or_b32_e32 v3, 0x60, v143
	s_movk_i32 s1, 0x68
	v_add_u32_e32 v15, 0x2200, v11
	v_mov_b32_e32 v16, 0x60
	v_bitop3_b32 v3, v3, v144, s1 bitop3:0x6c
	v_bitop3_b32 v16, v143, s1, v16 bitop3:0xc8
	v_lshl_add_u32 v108, v3, 1, v15
	v_or_b32_e32 v3, 0x70, v143
	s_movk_i32 s1, 0x78
	v_add_u32_e32 v100, v5, v0
	v_and_b32_e32 v5, 8, v196
	v_add_u32_e32 v17, 0x3300, v11
	v_bitop3_b32 v3, v3, v144, s1 bitop3:0x6c
	v_and_b32_e32 v7, 24, v146
	v_lshl_add_u32 v109, v3, 1, v17
	v_bitop3_b32 v3, v144, v5, 32 bitop3:0x36
	v_bitop3_b32 v9, v143, 40, 32 bitop3:0xc8
	v_lshl_add_u32 v110, v3, 1, v4
	v_bitop3_b32 v3, v144, v7, 32 bitop3:0x36
	v_bitop3_b32 v10, v143, 56, 48 bitop3:0xc8
	v_lshl_add_u32 v111, v3, 1, v6
	v_bitop3_b32 v3, v144, v9, 32 bitop3:0x36
	v_mov_b32_e32 v14, 0x50
	v_lshl_add_u32 v112, v3, 1, v8
	v_bitop3_b32 v3, v144, v10, 32 bitop3:0x36
	v_bitop3_b32 v14, v143, s0, v14 bitop3:0xc8
	v_lshl_add_u32 v113, v3, 1, v1
	v_bitop3_b32 v3, v144, v12, 32 bitop3:0x36
	v_mov_b32_e32 v18, 0x70
	v_lshl_add_u32 v114, v3, 1, v11
	v_bitop3_b32 v3, v144, v14, 32 bitop3:0x36
	v_bitop3_b32 v18, v143, s1, v18 bitop3:0xc8
	v_lshl_add_u32 v115, v3, 1, v13
	v_bitop3_b32 v3, v144, v16, 32 bitop3:0x36
	v_lshl_add_u32 v116, v3, 1, v15
	v_bitop3_b32 v3, v144, v18, 32 bitop3:0x36
	v_lshl_add_u32 v117, v3, 1, v17
	v_bitop3_b32 v3, v144, v5, 64 bitop3:0x36
	v_lshl_add_u32 v118, v3, 1, v4
	v_bitop3_b32 v3, v144, v7, 64 bitop3:0x36
	v_lshl_add_u32 v119, v3, 1, v6
	v_bitop3_b32 v3, v144, v9, 64 bitop3:0x36
	v_lshl_add_u32 v120, v3, 1, v8
	v_bitop3_b32 v3, v144, v10, 64 bitop3:0x36
	v_lshl_add_u32 v121, v3, 1, v1
	v_bitop3_b32 v3, v144, v12, 64 bitop3:0x36
	v_lshl_add_u32 v122, v3, 1, v11
	v_bitop3_b32 v3, v144, v14, 64 bitop3:0x36
	v_lshl_add_u32 v123, v3, 1, v13
	v_bitop3_b32 v3, v144, v16, 64 bitop3:0x36
	s_movk_i32 s0, 0x60
	v_lshl_add_u32 v124, v3, 1, v15
	v_bitop3_b32 v3, v144, v18, 64 bitop3:0x36
	v_lshl_add_u32 v125, v3, 1, v17
	v_bitop3_b32 v3, v144, v5, s0 bitop3:0x36
	v_lshl_add_u32 v126, v3, 1, v4
	v_bitop3_b32 v3, v144, v7, s0 bitop3:0x36
	v_lshl_add_u32 v127, v3, 1, v6
	v_bitop3_b32 v3, v144, v9, s0 bitop3:0x36
	v_lshl_add_u32 v128, v3, 1, v8
	v_bitop3_b32 v3, v144, v10, s0 bitop3:0x36
	v_lshl_add_u32 v129, v3, 1, v1
	v_bitop3_b32 v1, v144, v12, s0 bitop3:0x36
	v_lshl_add_u32 v130, v1, 1, v11
	v_bitop3_b32 v1, v144, v14, s0 bitop3:0x36
	v_lshl_add_u32 v131, v1, 1, v13
	v_bitop3_b32 v1, v144, v16, s0 bitop3:0x36
	v_lshlrev_b32_e32 v0, 7, v143
	s_waitcnt vmcnt(8)
	v_mov_b32_e32 v57, 0
	v_lshl_add_u32 v132, v1, 1, v15
	v_bitop3_b32 v1, v144, v18, s0 bitop3:0x36
	s_movk_i32 s0, 0x4200
	v_lshlrev_b32_e32 v56, 1, v144
	v_lshl_or_b32 v0, v142, 12, v0
	v_lshl_add_u32 v133, v1, 1, v17
	v_mad_u32_u24 v1, v142, s0, 16
	v_lshl_add_u64 v[4:5], s[88:89], 0, v[56:57]
	s_mov_b64 s[0:1], 0x224000
	v_lshlrev_b32_e32 v56, 4, v143
	s_mov_b64 s[70:71], s[6:7]
	v_or_b32_e32 v2, 0x800, v0
	v_lshlrev_b32_e32 v134, 5, v142
	v_add_u32_e32 v3, v1, v145
	v_mul_u32_u24_e32 v6, 0x210, v143
	v_lshl_add_u32 v1, v143, 5, v1
	v_mul_u32_u24_e32 v7, 0x210, v107
	v_lshl_add_u64 v[58:59], v[4:5], 0, s[0:1]
	v_lshl_add_u64 v[4:5], s[88:89], 0, v[56:57]
	s_mov_b64 s[0:1], 0x1840000
	s_mov_b64 s[68:69], s[4:5]
	s_mov_b64 s[74:75], s[10:11]
	v_lshlrev_b32_e32 v77, 3, v143
	v_lshrrev_b32_e32 v80, 4, v150
	v_lshrrev_b32_e32 v83, 4, v149
	v_lshrrev_b32_e32 v86, 4, v148
	v_or_b32_e32 v135, v134, v143
	v_or_b32_e32 v136, 4, v107
	v_or_b32_e32 v137, 8, v107
	v_or_b32_e32 v138, 12, v107
	v_or_b32_e32 v139, 16, v107
	v_or_b32_e32 v140, 20, v107
	v_or_b32_e32 v141, 24, v107
	v_or_b32_e32 v142, 28, v107
	v_lshl_add_u64 v[60:61], s[42:43], 0, v[56:57]
	v_lshl_add_u64 v[62:63], v[4:5], 0, s[0:1]
	s_lshl_b32 s2, s84, 7
	s_lshl_b32 s3, s92, 7
	s_lshl_b32 s4, s84, 4
	s_lshl_b32 s5, s92, 4
	s_movk_i32 s6, 0x1c00
	s_mov_b32 s1, 0
	v_lshlrev_b32_e32 v64, 1, v0
	v_lshlrev_b32_e32 v66, 1, v2
	v_add_u32_e32 v143, v3, v6
	v_add_u32_e32 v144, v1, v7
	s_mov_b32 s7, s84
